# PEER pass 2 (down projection) hand-written: rows double-buffered one token ahead, permlane32/16 swap + DPP transposing reduce; on top of the column-sliced pass 1
# speedup vs baseline: 1.0387x; 1.0180x over previous
.Lpv2:
	v_and_b32_e32 v5, 7, v167
	v_lshlrev_b32_e32 v1, 4, v5
	v_lshrrev_b32_e32 v4, 3, v167
	v_lshlrev_b32_e32 v3, 5, v5
	v_lshl_or_b32 v3, v4, 2, v3
	v_lshlrev_b32_e32 v4, 2, v4
	v_lshlrev_b32_e32 v6, 2, v167
	v_add_u32_e32 v12, 32, v4
	v_add_u32_e32 v13, 64, v4
	v_add_u32_e32 v14, 96, v4
	v_add_u32_e32 v15, 128, v4
	v_add_u32_e32 v16, 160, v4
	v_add_u32_e32 v17, 192, v4
	v_add_u32_e32 v18, 224, v4
	v_and_b32_e32 v7, 8, v167
	v_cmp_ne_u32_e64 s[30:31], 0, v7
	v_mov_b32_e32 v7, 0x26c08
	ds_read_b32 v8, v7
	ds_read_b32 v9, v7 offset:4
	v_add_u32_e32 v10, 0x670b800, v6
	global_load_dword v11, v10, s[66:67] sc1
	s_waitcnt vmcnt(0) lgkmcnt(0)
	v_readfirstlane_b32 s0, v8
	v_readfirstlane_b32 s1, v9
	v_cmp_ne_u32_e64 s[20:21], 0, v11
	s_nop 3
	s_and_b32 s20, s20, 0xffff
	s_bcnt1_i32_b32 s41, s20
	s_bfm_b32 s21, s0, 0
	s_and_b32 s21, s21, s20
	s_bcnt1_i32_b32 s40, s21
	s_nop 3
	v_readlane_b32 s39, v11, s0
	v_readfirstlane_b32 s20, v135
	s_nop 3
	s_lshl_b32 s39, s39, 3
	s_max_u32 s39, s39, 8
	s_max_u32 s41, s41, 1
	s_lshr_b32 s20, s20, 6
	s_lshl_b32 s1, s1, 3
	s_add_i32 s51, s1, s20
	s_add_u32 s42, s66, 0x20b6c000
	s_addc_u32 s43, s67, 0
	s_add_u32 s46, s66, 0x25f6c000
	s_addc_u32 s47, s67, 0
.Lpv2_part:
	s_cmp_gt_u32 s40, 7
	s_cbranch_scc1 .Lpv2_done
	s_lshl_b32 s0, s40, 21
	s_add_u32 s44, s66, s0
	s_addc_u32 s45, s67, 0
	s_add_u32 s44, s44, 0x4010000
	s_addc_u32 s45, s45, 0
	s_lshl_b32 s0, s40, 8
	s_add_u32 s48, s66, s0
	s_addc_u32 s49, s67, 0
	s_add_u32 s48, s48, 0x10b6c000
	s_addc_u32 s49, s49, 0
	s_mov_b32 s38, s51
	s_lshl_b32 s0, s38, 9
	v_add_u32_e32 v0, s0, v6
	global_load_dword v10, v0, s[42:43]
	global_load_dword v11, v0, s[42:43] offset:256
	global_load_dword v20, v0, s[46:47]
	global_load_dword v21, v0, s[46:47] offset:256
	s_waitcnt vmcnt(0)
	v_mov_b32_e32 v22, v20
	v_mov_b32_e32 v23, v21
	ds_bpermute_b32 v124, v4, v10
	ds_bpermute_b32 v125, v12, v10
	ds_bpermute_b32 v126, v13, v10
	ds_bpermute_b32 v127, v14, v10
	ds_bpermute_b32 v128, v15, v10
	ds_bpermute_b32 v129, v16, v10
	ds_bpermute_b32 v130, v17, v10
	ds_bpermute_b32 v131, v18, v10
	s_waitcnt lgkmcnt(0)
	v_lshl_add_u32 v124, v124, 7, v1
	v_lshl_add_u32 v125, v125, 7, v1
	v_lshl_add_u32 v126, v126, 7, v1
	v_lshl_add_u32 v127, v127, 7, v1
	v_lshl_add_u32 v128, v128, 7, v1
	v_lshl_add_u32 v129, v129, 7, v1
	v_lshl_add_u32 v130, v130, 7, v1
	v_lshl_add_u32 v131, v131, 7, v1
	global_load_dwordx4 v[44:47], v124, s[44:45]
	global_load_dwordx4 v[48:51], v125, s[44:45]
	global_load_dwordx4 v[52:55], v126, s[44:45]
	global_load_dwordx4 v[56:59], v127, s[44:45]
	global_load_dwordx4 v[60:63], v128, s[44:45]
	global_load_dwordx4 v[64:67], v129, s[44:45]
	global_load_dwordx4 v[68:71], v130, s[44:45]
	global_load_dwordx4 v[72:75], v131, s[44:45]
	ds_bpermute_b32 v124, v4, v11
	ds_bpermute_b32 v125, v12, v11
	ds_bpermute_b32 v126, v13, v11
	ds_bpermute_b32 v127, v14, v11
	ds_bpermute_b32 v128, v15, v11
	ds_bpermute_b32 v129, v16, v11
	ds_bpermute_b32 v130, v17, v11
	ds_bpermute_b32 v131, v18, v11
	s_waitcnt lgkmcnt(0)
	v_lshl_add_u32 v124, v124, 7, v1
	v_lshl_add_u32 v125, v125, 7, v1
	v_lshl_add_u32 v126, v126, 7, v1
	v_lshl_add_u32 v127, v127, 7, v1
	v_lshl_add_u32 v128, v128, 7, v1
	v_lshl_add_u32 v129, v129, 7, v1
	v_lshl_add_u32 v130, v130, 7, v1
	v_lshl_add_u32 v131, v131, 7, v1
	global_load_dwordx4 v[76:79], v124, s[44:45]
	global_load_dwordx4 v[80:83], v125, s[44:45]
	global_load_dwordx4 v[84:87], v126, s[44:45]
	global_load_dwordx4 v[88:91], v127, s[44:45]
	global_load_dwordx4 v[92:95], v128, s[44:45]
	global_load_dwordx4 v[96:99], v129, s[44:45]
	global_load_dwordx4 v[100:103], v130, s[44:45]
	global_load_dwordx4 v[104:107], v131, s[44:45]
	s_add_i32 s1, s38, s39
	s_min_u32 s1, s1, 0xffff
	s_lshl_b32 s0, s1, 9
	v_add_u32_e32 v0, s0, v6
	global_load_dword v10, v0, s[42:43]
	global_load_dword v11, v0, s[42:43] offset:256
	global_load_dword v20, v0, s[46:47]
	global_load_dword v21, v0, s[46:47] offset:256
	s_waitcnt vmcnt(0)
	s_branch .Lpv2_tokA_in

.Lpv2_tokA_in:
	v_mov_b32_e32 v24, v20
	v_mov_b32_e32 v25, v21
	ds_bpermute_b32 v124, v4, v10
	ds_bpermute_b32 v125, v12, v10
	ds_bpermute_b32 v126, v13, v10
	ds_bpermute_b32 v127, v14, v10
	ds_bpermute_b32 v128, v15, v10
	ds_bpermute_b32 v129, v16, v10
	ds_bpermute_b32 v130, v17, v10
	ds_bpermute_b32 v131, v18, v10
	s_waitcnt lgkmcnt(0)
	v_lshl_add_u32 v124, v124, 7, v1
	v_lshl_add_u32 v125, v125, 7, v1
	v_lshl_add_u32 v126, v126, 7, v1
	v_lshl_add_u32 v127, v127, 7, v1
	v_lshl_add_u32 v128, v128, 7, v1
	v_lshl_add_u32 v129, v129, 7, v1
	v_lshl_add_u32 v130, v130, 7, v1
	v_lshl_add_u32 v131, v131, 7, v1
	global_load_dwordx4 v[198:201], v124, s[44:45]
	global_load_dwordx4 v[202:205], v125, s[44:45]
	global_load_dwordx4 v[206:209], v126, s[44:45]
	global_load_dwordx4 v[210:213], v127, s[44:45]
	global_load_dwordx4 v[214:217], v128, s[44:45]
	global_load_dwordx4 v[218:221], v129, s[44:45]
	global_load_dwordx4 v[222:225], v130, s[44:45]
	global_load_dwordx4 v[226:229], v131, s[44:45]
	ds_bpermute_b32 v124, v4, v11
	ds_bpermute_b32 v125, v12, v11
	ds_bpermute_b32 v126, v13, v11
	ds_bpermute_b32 v127, v14, v11
	ds_bpermute_b32 v128, v15, v11
	ds_bpermute_b32 v129, v16, v11
	ds_bpermute_b32 v130, v17, v11
	ds_bpermute_b32 v131, v18, v11
	s_waitcnt lgkmcnt(0)
	v_lshl_add_u32 v124, v124, 7, v1
	v_lshl_add_u32 v125, v125, 7, v1
	v_lshl_add_u32 v126, v126, 7, v1
	v_lshl_add_u32 v127, v127, 7, v1
	v_lshl_add_u32 v128, v128, 7, v1
	v_lshl_add_u32 v129, v129, 7, v1
	v_lshl_add_u32 v130, v130, 7, v1
	v_lshl_add_u32 v131, v131, 7, v1
	global_load_dwordx4 v[230:233], v124, s[44:45]
	global_load_dwordx4 v[234:237], v125, s[44:45]
	global_load_dwordx4 v[138:141], v126, s[44:45]
	global_load_dwordx4 v[142:145], v127, s[44:45]
	global_load_dwordx4 v[146:149], v128, s[44:45]
	global_load_dwordx4 v[150:153], v129, s[44:45]
	global_load_dwordx4 v[154:157], v130, s[44:45]
	global_load_dwordx4 v[158:161], v131, s[44:45]
	s_lshl_b32 s1, s39, 1
	s_add_i32 s1, s1, s38
	s_min_u32 s1, s1, 0xffff
	s_lshl_b32 s0, s1, 9
	v_add_u32_e32 v0, s0, v6
	global_load_dword v10, v0, s[42:43]
	global_load_dword v11, v0, s[42:43] offset:256
	global_load_dword v20, v0, s[46:47]
	global_load_dword v21, v0, s[46:47] offset:256
	ds_bpermute_b32 v238, v4, v22
	ds_bpermute_b32 v239, v12, v22
	ds_bpermute_b32 v240, v13, v22
	ds_bpermute_b32 v241, v14, v22
	ds_bpermute_b32 v242, v15, v22
	ds_bpermute_b32 v243, v16, v22
	ds_bpermute_b32 v244, v17, v22
	ds_bpermute_b32 v245, v18, v22
	ds_bpermute_b32 v108, v4, v23
	ds_bpermute_b32 v109, v12, v23
	ds_bpermute_b32 v110, v13, v23
	ds_bpermute_b32 v111, v14, v23
	ds_bpermute_b32 v112, v15, v23
	ds_bpermute_b32 v113, v16, v23
	ds_bpermute_b32 v114, v17, v23
	ds_bpermute_b32 v115, v18, v23
	s_waitcnt lgkmcnt(0)
	v_cvt_pk_f32_fp8_e32 v[118:119], v44
	v_cvt_pk_f32_fp8_sdwa v[120:121], v44 src0_sel:WORD_1
	s_nop 0
	v_pk_mul_f32 v[28:29], v[118:119], v[238:239] op_sel_hi:[1,0]
	v_cvt_pk_f32_fp8_e32 v[118:119], v45
	v_pk_mul_f32 v[30:31], v[120:121], v[238:239] op_sel_hi:[1,0]
	v_cvt_pk_f32_fp8_sdwa v[120:121], v45 src0_sel:WORD_1
	v_pk_mul_f32 v[32:33], v[118:119], v[238:239] op_sel_hi:[1,0]
	v_cvt_pk_f32_fp8_e32 v[118:119], v46
	v_pk_mul_f32 v[34:35], v[120:121], v[238:239] op_sel_hi:[1,0]
	v_cvt_pk_f32_fp8_sdwa v[120:121], v46 src0_sel:WORD_1
	v_pk_mul_f32 v[36:37], v[118:119], v[238:239] op_sel_hi:[1,0]
	v_cvt_pk_f32_fp8_e32 v[118:119], v47
	v_pk_mul_f32 v[38:39], v[120:121], v[238:239] op_sel_hi:[1,0]
	v_cvt_pk_f32_fp8_sdwa v[120:121], v47 src0_sel:WORD_1
	v_pk_mul_f32 v[40:41], v[118:119], v[238:239] op_sel_hi:[1,0]
	s_nop 0
	v_pk_mul_f32 v[42:43], v[120:121], v[238:239] op_sel_hi:[1,0]
	v_cvt_pk_f32_fp8_e32 v[118:119], v48
	v_cvt_pk_f32_fp8_sdwa v[120:121], v48 src0_sel:WORD_1
	s_nop 0
	v_pk_fma_f32 v[28:29], v[118:119], v[238:239], v[28:29] op_sel:[0,1,0] op_sel_hi:[1,1,1]
	v_cvt_pk_f32_fp8_e32 v[118:119], v49
	v_pk_fma_f32 v[30:31], v[120:121], v[238:239], v[30:31] op_sel:[0,1,0] op_sel_hi:[1,1,1]
	v_cvt_pk_f32_fp8_sdwa v[120:121], v49 src0_sel:WORD_1
	v_pk_fma_f32 v[32:33], v[118:119], v[238:239], v[32:33] op_sel:[0,1,0] op_sel_hi:[1,1,1]
	v_cvt_pk_f32_fp8_e32 v[118:119], v50
	v_pk_fma_f32 v[34:35], v[120:121], v[238:239], v[34:35] op_sel:[0,1,0] op_sel_hi:[1,1,1]
	v_cvt_pk_f32_fp8_sdwa v[120:121], v50 src0_sel:WORD_1
	v_pk_fma_f32 v[36:37], v[118:119], v[238:239], v[36:37] op_sel:[0,1,0] op_sel_hi:[1,1,1]
	v_cvt_pk_f32_fp8_e32 v[118:119], v51
	v_pk_fma_f32 v[38:39], v[120:121], v[238:239], v[38:39] op_sel:[0,1,0] op_sel_hi:[1,1,1]
	v_cvt_pk_f32_fp8_sdwa v[120:121], v51 src0_sel:WORD_1
	v_pk_fma_f32 v[40:41], v[118:119], v[238:239], v[40:41] op_sel:[0,1,0] op_sel_hi:[1,1,1]
	s_nop 0
	v_pk_fma_f32 v[42:43], v[120:121], v[238:239], v[42:43] op_sel:[0,1,0] op_sel_hi:[1,1,1]
	v_cvt_pk_f32_fp8_e32 v[118:119], v52
	v_cvt_pk_f32_fp8_sdwa v[120:121], v52 src0_sel:WORD_1
	s_nop 0
	v_pk_fma_f32 v[28:29], v[118:119], v[240:241], v[28:29] op_sel_hi:[1,0,1]
	v_cvt_pk_f32_fp8_e32 v[118:119], v53
	v_pk_fma_f32 v[30:31], v[120:121], v[240:241], v[30:31] op_sel_hi:[1,0,1]
	v_cvt_pk_f32_fp8_sdwa v[120:121], v53 src0_sel:WORD_1
	v_pk_fma_f32 v[32:33], v[118:119], v[240:241], v[32:33] op_sel_hi:[1,0,1]
	v_cvt_pk_f32_fp8_e32 v[118:119], v54
	v_pk_fma_f32 v[34:35], v[120:121], v[240:241], v[34:35] op_sel_hi:[1,0,1]
	v_cvt_pk_f32_fp8_sdwa v[120:121], v54 src0_sel:WORD_1
	v_pk_fma_f32 v[36:37], v[118:119], v[240:241], v[36:37] op_sel_hi:[1,0,1]
	v_cvt_pk_f32_fp8_e32 v[118:119], v55
	v_pk_fma_f32 v[38:39], v[120:121], v[240:241], v[38:39] op_sel_hi:[1,0,1]
	v_cvt_pk_f32_fp8_sdwa v[120:121], v55 src0_sel:WORD_1
	v_pk_fma_f32 v[40:41], v[118:119], v[240:241], v[40:41] op_sel_hi:[1,0,1]
	s_nop 0
	v_pk_fma_f32 v[42:43], v[120:121], v[240:241], v[42:43] op_sel_hi:[1,0,1]
	v_cvt_pk_f32_fp8_e32 v[118:119], v56
	v_cvt_pk_f32_fp8_sdwa v[120:121], v56 src0_sel:WORD_1
	s_nop 0
	v_pk_fma_f32 v[28:29], v[118:119], v[240:241], v[28:29] op_sel:[0,1,0] op_sel_hi:[1,1,1]
	v_cvt_pk_f32_fp8_e32 v[118:119], v57
	v_pk_fma_f32 v[30:31], v[120:121], v[240:241], v[30:31] op_sel:[0,1,0] op_sel_hi:[1,1,1]
	v_cvt_pk_f32_fp8_sdwa v[120:121], v57 src0_sel:WORD_1
	v_pk_fma_f32 v[32:33], v[118:119], v[240:241], v[32:33] op_sel:[0,1,0] op_sel_hi:[1,1,1]
	v_cvt_pk_f32_fp8_e32 v[118:119], v58
	v_pk_fma_f32 v[34:35], v[120:121], v[240:241], v[34:35] op_sel:[0,1,0] op_sel_hi:[1,1,1]
	v_cvt_pk_f32_fp8_sdwa v[120:121], v58 src0_sel:WORD_1
	v_pk_fma_f32 v[36:37], v[118:119], v[240:241], v[36:37] op_sel:[0,1,0] op_sel_hi:[1,1,1]
	v_cvt_pk_f32_fp8_e32 v[118:119], v59
	v_pk_fma_f32 v[38:39], v[120:121], v[240:241], v[38:39] op_sel:[0,1,0] op_sel_hi:[1,1,1]
	v_cvt_pk_f32_fp8_sdwa v[120:121], v59 src0_sel:WORD_1
	v_pk_fma_f32 v[40:41], v[118:119], v[240:241], v[40:41] op_sel:[0,1,0] op_sel_hi:[1,1,1]
	s_nop 0
	v_pk_fma_f32 v[42:43], v[120:121], v[240:241], v[42:43] op_sel:[0,1,0] op_sel_hi:[1,1,1]
	v_cvt_pk_f32_fp8_e32 v[118:119], v60
	v_cvt_pk_f32_fp8_sdwa v[120:121], v60 src0_sel:WORD_1
	s_nop 0
	v_pk_fma_f32 v[28:29], v[118:119], v[242:243], v[28:29] op_sel_hi:[1,0,1]
	v_cvt_pk_f32_fp8_e32 v[118:119], v61
	v_pk_fma_f32 v[30:31], v[120:121], v[242:243], v[30:31] op_sel_hi:[1,0,1]
	v_cvt_pk_f32_fp8_sdwa v[120:121], v61 src0_sel:WORD_1
	v_pk_fma_f32 v[32:33], v[118:119], v[242:243], v[32:33] op_sel_hi:[1,0,1]
	v_cvt_pk_f32_fp8_e32 v[118:119], v62
	v_pk_fma_f32 v[34:35], v[120:121], v[242:243], v[34:35] op_sel_hi:[1,0,1]
	v_cvt_pk_f32_fp8_sdwa v[120:121], v62 src0_sel:WORD_1
	v_pk_fma_f32 v[36:37], v[118:119], v[242:243], v[36:37] op_sel_hi:[1,0,1]
	v_cvt_pk_f32_fp8_e32 v[118:119], v63
	v_pk_fma_f32 v[38:39], v[120:121], v[242:243], v[38:39] op_sel_hi:[1,0,1]
	v_cvt_pk_f32_fp8_sdwa v[120:121], v63 src0_sel:WORD_1
	v_pk_fma_f32 v[40:41], v[118:119], v[242:243], v[40:41] op_sel_hi:[1,0,1]
	s_nop 0
	v_pk_fma_f32 v[42:43], v[120:121], v[242:243], v[42:43] op_sel_hi:[1,0,1]
	v_cvt_pk_f32_fp8_e32 v[118:119], v64
	v_cvt_pk_f32_fp8_sdwa v[120:121], v64 src0_sel:WORD_1
	s_nop 0
	v_pk_fma_f32 v[28:29], v[118:119], v[242:243], v[28:29] op_sel:[0,1,0] op_sel_hi:[1,1,1]
	v_cvt_pk_f32_fp8_e32 v[118:119], v65
	v_pk_fma_f32 v[30:31], v[120:121], v[242:243], v[30:31] op_sel:[0,1,0] op_sel_hi:[1,1,1]
	v_cvt_pk_f32_fp8_sdwa v[120:121], v65 src0_sel:WORD_1
	v_pk_fma_f32 v[32:33], v[118:119], v[242:243], v[32:33] op_sel:[0,1,0] op_sel_hi:[1,1,1]
	v_cvt_pk_f32_fp8_e32 v[118:119], v66
	v_pk_fma_f32 v[34:35], v[120:121], v[242:243], v[34:35] op_sel:[0,1,0] op_sel_hi:[1,1,1]
	v_cvt_pk_f32_fp8_sdwa v[120:121], v66 src0_sel:WORD_1
	v_pk_fma_f32 v[36:37], v[118:119], v[242:243], v[36:37] op_sel:[0,1,0] op_sel_hi:[1,1,1]
	v_cvt_pk_f32_fp8_e32 v[118:119], v67
	v_pk_fma_f32 v[38:39], v[120:121], v[242:243], v[38:39] op_sel:[0,1,0] op_sel_hi:[1,1,1]
	v_cvt_pk_f32_fp8_sdwa v[120:121], v67 src0_sel:WORD_1
	v_pk_fma_f32 v[40:41], v[118:119], v[242:243], v[40:41] op_sel:[0,1,0] op_sel_hi:[1,1,1]
	s_nop 0
	v_pk_fma_f32 v[42:43], v[120:121], v[242:243], v[42:43] op_sel:[0,1,0] op_sel_hi:[1,1,1]
	v_cvt_pk_f32_fp8_e32 v[118:119], v68
	v_cvt_pk_f32_fp8_sdwa v[120:121], v68 src0_sel:WORD_1
	s_nop 0
	v_pk_fma_f32 v[28:29], v[118:119], v[244:245], v[28:29] op_sel_hi:[1,0,1]
	v_cvt_pk_f32_fp8_e32 v[118:119], v69
	v_pk_fma_f32 v[30:31], v[120:121], v[244:245], v[30:31] op_sel_hi:[1,0,1]
	v_cvt_pk_f32_fp8_sdwa v[120:121], v69 src0_sel:WORD_1
	v_pk_fma_f32 v[32:33], v[118:119], v[244:245], v[32:33] op_sel_hi:[1,0,1]
	v_cvt_pk_f32_fp8_e32 v[118:119], v70
	v_pk_fma_f32 v[34:35], v[120:121], v[244:245], v[34:35] op_sel_hi:[1,0,1]
	v_cvt_pk_f32_fp8_sdwa v[120:121], v70 src0_sel:WORD_1
	v_pk_fma_f32 v[36:37], v[118:119], v[244:245], v[36:37] op_sel_hi:[1,0,1]
	v_cvt_pk_f32_fp8_e32 v[118:119], v71
	v_pk_fma_f32 v[38:39], v[120:121], v[244:245], v[38:39] op_sel_hi:[1,0,1]
	v_cvt_pk_f32_fp8_sdwa v[120:121], v71 src0_sel:WORD_1
	v_pk_fma_f32 v[40:41], v[118:119], v[244:245], v[40:41] op_sel_hi:[1,0,1]
	s_nop 0
	v_pk_fma_f32 v[42:43], v[120:121], v[244:245], v[42:43] op_sel_hi:[1,0,1]
	v_cvt_pk_f32_fp8_e32 v[118:119], v72
	v_cvt_pk_f32_fp8_sdwa v[120:121], v72 src0_sel:WORD_1
	s_nop 0
	v_pk_fma_f32 v[28:29], v[118:119], v[244:245], v[28:29] op_sel:[0,1,0] op_sel_hi:[1,1,1]
	v_cvt_pk_f32_fp8_e32 v[118:119], v73
	v_pk_fma_f32 v[30:31], v[120:121], v[244:245], v[30:31] op_sel:[0,1,0] op_sel_hi:[1,1,1]
	v_cvt_pk_f32_fp8_sdwa v[120:121], v73 src0_sel:WORD_1
	v_pk_fma_f32 v[32:33], v[118:119], v[244:245], v[32:33] op_sel:[0,1,0] op_sel_hi:[1,1,1]
	v_cvt_pk_f32_fp8_e32 v[118:119], v74
	v_pk_fma_f32 v[34:35], v[120:121], v[244:245], v[34:35] op_sel:[0,1,0] op_sel_hi:[1,1,1]
	v_cvt_pk_f32_fp8_sdwa v[120:121], v74 src0_sel:WORD_1
	v_pk_fma_f32 v[36:37], v[118:119], v[244:245], v[36:37] op_sel:[0,1,0] op_sel_hi:[1,1,1]
	v_cvt_pk_f32_fp8_e32 v[118:119], v75
	v_pk_fma_f32 v[38:39], v[120:121], v[244:245], v[38:39] op_sel:[0,1,0] op_sel_hi:[1,1,1]
	v_cvt_pk_f32_fp8_sdwa v[120:121], v75 src0_sel:WORD_1
	v_pk_fma_f32 v[40:41], v[118:119], v[244:245], v[40:41] op_sel:[0,1,0] op_sel_hi:[1,1,1]
	s_nop 0
	v_pk_fma_f32 v[42:43], v[120:121], v[244:245], v[42:43] op_sel:[0,1,0] op_sel_hi:[1,1,1]
	v_cvt_pk_f32_fp8_e32 v[118:119], v76
	v_cvt_pk_f32_fp8_sdwa v[120:121], v76 src0_sel:WORD_1
	s_nop 0
	v_pk_fma_f32 v[28:29], v[118:119], v[108:109], v[28:29] op_sel_hi:[1,0,1]
	v_cvt_pk_f32_fp8_e32 v[118:119], v77
	v_pk_fma_f32 v[30:31], v[120:121], v[108:109], v[30:31] op_sel_hi:[1,0,1]
	v_cvt_pk_f32_fp8_sdwa v[120:121], v77 src0_sel:WORD_1
	v_pk_fma_f32 v[32:33], v[118:119], v[108:109], v[32:33] op_sel_hi:[1,0,1]
	v_cvt_pk_f32_fp8_e32 v[118:119], v78
	v_pk_fma_f32 v[34:35], v[120:121], v[108:109], v[34:35] op_sel_hi:[1,0,1]
	v_cvt_pk_f32_fp8_sdwa v[120:121], v78 src0_sel:WORD_1
	v_pk_fma_f32 v[36:37], v[118:119], v[108:109], v[36:37] op_sel_hi:[1,0,1]
	v_cvt_pk_f32_fp8_e32 v[118:119], v79
	v_pk_fma_f32 v[38:39], v[120:121], v[108:109], v[38:39] op_sel_hi:[1,0,1]
	v_cvt_pk_f32_fp8_sdwa v[120:121], v79 src0_sel:WORD_1
	v_pk_fma_f32 v[40:41], v[118:119], v[108:109], v[40:41] op_sel_hi:[1,0,1]
	s_nop 0
	v_pk_fma_f32 v[42:43], v[120:121], v[108:109], v[42:43] op_sel_hi:[1,0,1]
	v_cvt_pk_f32_fp8_e32 v[118:119], v80
	v_cvt_pk_f32_fp8_sdwa v[120:121], v80 src0_sel:WORD_1
	s_nop 0
	v_pk_fma_f32 v[28:29], v[118:119], v[108:109], v[28:29] op_sel:[0,1,0] op_sel_hi:[1,1,1]
	v_cvt_pk_f32_fp8_e32 v[118:119], v81
	v_pk_fma_f32 v[30:31], v[120:121], v[108:109], v[30:31] op_sel:[0,1,0] op_sel_hi:[1,1,1]
	v_cvt_pk_f32_fp8_sdwa v[120:121], v81 src0_sel:WORD_1
	v_pk_fma_f32 v[32:33], v[118:119], v[108:109], v[32:33] op_sel:[0,1,0] op_sel_hi:[1,1,1]
	v_cvt_pk_f32_fp8_e32 v[118:119], v82
	v_pk_fma_f32 v[34:35], v[120:121], v[108:109], v[34:35] op_sel:[0,1,0] op_sel_hi:[1,1,1]
	v_cvt_pk_f32_fp8_sdwa v[120:121], v82 src0_sel:WORD_1
	v_pk_fma_f32 v[36:37], v[118:119], v[108:109], v[36:37] op_sel:[0,1,0] op_sel_hi:[1,1,1]
	v_cvt_pk_f32_fp8_e32 v[118:119], v83
	v_pk_fma_f32 v[38:39], v[120:121], v[108:109], v[38:39] op_sel:[0,1,0] op_sel_hi:[1,1,1]
	v_cvt_pk_f32_fp8_sdwa v[120:121], v83 src0_sel:WORD_1
	v_pk_fma_f32 v[40:41], v[118:119], v[108:109], v[40:41] op_sel:[0,1,0] op_sel_hi:[1,1,1]
	s_nop 0
	v_pk_fma_f32 v[42:43], v[120:121], v[108:109], v[42:43] op_sel:[0,1,0] op_sel_hi:[1,1,1]
	v_cvt_pk_f32_fp8_e32 v[118:119], v84
	v_cvt_pk_f32_fp8_sdwa v[120:121], v84 src0_sel:WORD_1
	s_nop 0
	v_pk_fma_f32 v[28:29], v[118:119], v[110:111], v[28:29] op_sel_hi:[1,0,1]
	v_cvt_pk_f32_fp8_e32 v[118:119], v85
	v_pk_fma_f32 v[30:31], v[120:121], v[110:111], v[30:31] op_sel_hi:[1,0,1]
	v_cvt_pk_f32_fp8_sdwa v[120:121], v85 src0_sel:WORD_1
	v_pk_fma_f32 v[32:33], v[118:119], v[110:111], v[32:33] op_sel_hi:[1,0,1]
	v_cvt_pk_f32_fp8_e32 v[118:119], v86
	v_pk_fma_f32 v[34:35], v[120:121], v[110:111], v[34:35] op_sel_hi:[1,0,1]
	v_cvt_pk_f32_fp8_sdwa v[120:121], v86 src0_sel:WORD_1
	v_pk_fma_f32 v[36:37], v[118:119], v[110:111], v[36:37] op_sel_hi:[1,0,1]
	v_cvt_pk_f32_fp8_e32 v[118:119], v87
	v_pk_fma_f32 v[38:39], v[120:121], v[110:111], v[38:39] op_sel_hi:[1,0,1]
	v_cvt_pk_f32_fp8_sdwa v[120:121], v87 src0_sel:WORD_1
	v_pk_fma_f32 v[40:41], v[118:119], v[110:111], v[40:41] op_sel_hi:[1,0,1]
	s_nop 0
	v_pk_fma_f32 v[42:43], v[120:121], v[110:111], v[42:43] op_sel_hi:[1,0,1]
	v_cvt_pk_f32_fp8_e32 v[118:119], v88
	v_cvt_pk_f32_fp8_sdwa v[120:121], v88 src0_sel:WORD_1
	s_nop 0
	v_pk_fma_f32 v[28:29], v[118:119], v[110:111], v[28:29] op_sel:[0,1,0] op_sel_hi:[1,1,1]
	v_cvt_pk_f32_fp8_e32 v[118:119], v89
	v_pk_fma_f32 v[30:31], v[120:121], v[110:111], v[30:31] op_sel:[0,1,0] op_sel_hi:[1,1,1]
	v_cvt_pk_f32_fp8_sdwa v[120:121], v89 src0_sel:WORD_1
	v_pk_fma_f32 v[32:33], v[118:119], v[110:111], v[32:33] op_sel:[0,1,0] op_sel_hi:[1,1,1]
	v_cvt_pk_f32_fp8_e32 v[118:119], v90
	v_pk_fma_f32 v[34:35], v[120:121], v[110:111], v[34:35] op_sel:[0,1,0] op_sel_hi:[1,1,1]
	v_cvt_pk_f32_fp8_sdwa v[120:121], v90 src0_sel:WORD_1
	v_pk_fma_f32 v[36:37], v[118:119], v[110:111], v[36:37] op_sel:[0,1,0] op_sel_hi:[1,1,1]
	v_cvt_pk_f32_fp8_e32 v[118:119], v91
	v_pk_fma_f32 v[38:39], v[120:121], v[110:111], v[38:39] op_sel:[0,1,0] op_sel_hi:[1,1,1]
	v_cvt_pk_f32_fp8_sdwa v[120:121], v91 src0_sel:WORD_1
	v_pk_fma_f32 v[40:41], v[118:119], v[110:111], v[40:41] op_sel:[0,1,0] op_sel_hi:[1,1,1]
	s_nop 0
	v_pk_fma_f32 v[42:43], v[120:121], v[110:111], v[42:43] op_sel:[0,1,0] op_sel_hi:[1,1,1]
	v_cvt_pk_f32_fp8_e32 v[118:119], v92
	v_cvt_pk_f32_fp8_sdwa v[120:121], v92 src0_sel:WORD_1
	s_nop 0
	v_pk_fma_f32 v[28:29], v[118:119], v[112:113], v[28:29] op_sel_hi:[1,0,1]
	v_cvt_pk_f32_fp8_e32 v[118:119], v93
	v_pk_fma_f32 v[30:31], v[120:121], v[112:113], v[30:31] op_sel_hi:[1,0,1]
	v_cvt_pk_f32_fp8_sdwa v[120:121], v93 src0_sel:WORD_1
	v_pk_fma_f32 v[32:33], v[118:119], v[112:113], v[32:33] op_sel_hi:[1,0,1]
	v_cvt_pk_f32_fp8_e32 v[118:119], v94
	v_pk_fma_f32 v[34:35], v[120:121], v[112:113], v[34:35] op_sel_hi:[1,0,1]
	v_cvt_pk_f32_fp8_sdwa v[120:121], v94 src0_sel:WORD_1
	v_pk_fma_f32 v[36:37], v[118:119], v[112:113], v[36:37] op_sel_hi:[1,0,1]
	v_cvt_pk_f32_fp8_e32 v[118:119], v95
	v_pk_fma_f32 v[38:39], v[120:121], v[112:113], v[38:39] op_sel_hi:[1,0,1]
	v_cvt_pk_f32_fp8_sdwa v[120:121], v95 src0_sel:WORD_1
	v_pk_fma_f32 v[40:41], v[118:119], v[112:113], v[40:41] op_sel_hi:[1,0,1]
	s_nop 0
	v_pk_fma_f32 v[42:43], v[120:121], v[112:113], v[42:43] op_sel_hi:[1,0,1]
	v_cvt_pk_f32_fp8_e32 v[118:119], v96
	v_cvt_pk_f32_fp8_sdwa v[120:121], v96 src0_sel:WORD_1
	s_nop 0
	v_pk_fma_f32 v[28:29], v[118:119], v[112:113], v[28:29] op_sel:[0,1,0] op_sel_hi:[1,1,1]
	v_cvt_pk_f32_fp8_e32 v[118:119], v97
	v_pk_fma_f32 v[30:31], v[120:121], v[112:113], v[30:31] op_sel:[0,1,0] op_sel_hi:[1,1,1]
	v_cvt_pk_f32_fp8_sdwa v[120:121], v97 src0_sel:WORD_1
	v_pk_fma_f32 v[32:33], v[118:119], v[112:113], v[32:33] op_sel:[0,1,0] op_sel_hi:[1,1,1]
	v_cvt_pk_f32_fp8_e32 v[118:119], v98
	v_pk_fma_f32 v[34:35], v[120:121], v[112:113], v[34:35] op_sel:[0,1,0] op_sel_hi:[1,1,1]
	v_cvt_pk_f32_fp8_sdwa v[120:121], v98 src0_sel:WORD_1
	v_pk_fma_f32 v[36:37], v[118:119], v[112:113], v[36:37] op_sel:[0,1,0] op_sel_hi:[1,1,1]
	v_cvt_pk_f32_fp8_e32 v[118:119], v99
	v_pk_fma_f32 v[38:39], v[120:121], v[112:113], v[38:39] op_sel:[0,1,0] op_sel_hi:[1,1,1]
	v_cvt_pk_f32_fp8_sdwa v[120:121], v99 src0_sel:WORD_1
	v_pk_fma_f32 v[40:41], v[118:119], v[112:113], v[40:41] op_sel:[0,1,0] op_sel_hi:[1,1,1]
	s_nop 0
	v_pk_fma_f32 v[42:43], v[120:121], v[112:113], v[42:43] op_sel:[0,1,0] op_sel_hi:[1,1,1]
	v_cvt_pk_f32_fp8_e32 v[118:119], v100
	v_cvt_pk_f32_fp8_sdwa v[120:121], v100 src0_sel:WORD_1
	s_nop 0
	v_pk_fma_f32 v[28:29], v[118:119], v[114:115], v[28:29] op_sel_hi:[1,0,1]
	v_cvt_pk_f32_fp8_e32 v[118:119], v101
	v_pk_fma_f32 v[30:31], v[120:121], v[114:115], v[30:31] op_sel_hi:[1,0,1]
	v_cvt_pk_f32_fp8_sdwa v[120:121], v101 src0_sel:WORD_1
	v_pk_fma_f32 v[32:33], v[118:119], v[114:115], v[32:33] op_sel_hi:[1,0,1]
	v_cvt_pk_f32_fp8_e32 v[118:119], v102
	v_pk_fma_f32 v[34:35], v[120:121], v[114:115], v[34:35] op_sel_hi:[1,0,1]
	v_cvt_pk_f32_fp8_sdwa v[120:121], v102 src0_sel:WORD_1
	v_pk_fma_f32 v[36:37], v[118:119], v[114:115], v[36:37] op_sel_hi:[1,0,1]
	v_cvt_pk_f32_fp8_e32 v[118:119], v103
	v_pk_fma_f32 v[38:39], v[120:121], v[114:115], v[38:39] op_sel_hi:[1,0,1]
	v_cvt_pk_f32_fp8_sdwa v[120:121], v103 src0_sel:WORD_1
	v_pk_fma_f32 v[40:41], v[118:119], v[114:115], v[40:41] op_sel_hi:[1,0,1]
	s_nop 0
	v_pk_fma_f32 v[42:43], v[120:121], v[114:115], v[42:43] op_sel_hi:[1,0,1]
	v_cvt_pk_f32_fp8_e32 v[118:119], v104
	v_cvt_pk_f32_fp8_sdwa v[120:121], v104 src0_sel:WORD_1
	s_nop 0
	v_pk_fma_f32 v[28:29], v[118:119], v[114:115], v[28:29] op_sel:[0,1,0] op_sel_hi:[1,1,1]
	v_cvt_pk_f32_fp8_e32 v[118:119], v105
	v_pk_fma_f32 v[30:31], v[120:121], v[114:115], v[30:31] op_sel:[0,1,0] op_sel_hi:[1,1,1]
	v_cvt_pk_f32_fp8_sdwa v[120:121], v105 src0_sel:WORD_1
	v_pk_fma_f32 v[32:33], v[118:119], v[114:115], v[32:33] op_sel:[0,1,0] op_sel_hi:[1,1,1]
	v_cvt_pk_f32_fp8_e32 v[118:119], v106
	v_pk_fma_f32 v[34:35], v[120:121], v[114:115], v[34:35] op_sel:[0,1,0] op_sel_hi:[1,1,1]
	v_cvt_pk_f32_fp8_sdwa v[120:121], v106 src0_sel:WORD_1
	v_pk_fma_f32 v[36:37], v[118:119], v[114:115], v[36:37] op_sel:[0,1,0] op_sel_hi:[1,1,1]
	v_cvt_pk_f32_fp8_e32 v[118:119], v107
	v_pk_fma_f32 v[38:39], v[120:121], v[114:115], v[38:39] op_sel:[0,1,0] op_sel_hi:[1,1,1]
	v_cvt_pk_f32_fp8_sdwa v[120:121], v107 src0_sel:WORD_1
	v_pk_fma_f32 v[40:41], v[118:119], v[114:115], v[40:41] op_sel:[0,1,0] op_sel_hi:[1,1,1]
	s_nop 0
	v_pk_fma_f32 v[42:43], v[120:121], v[114:115], v[42:43] op_sel:[0,1,0] op_sel_hi:[1,1,1]
	s_nop 1
	v_permlane32_swap_b32_e32 v28, v36
	v_permlane32_swap_b32_e32 v29, v37
	v_permlane32_swap_b32_e32 v30, v38
	v_permlane32_swap_b32_e32 v31, v39
	v_permlane32_swap_b32_e32 v32, v40
	v_permlane32_swap_b32_e32 v33, v41
	v_permlane32_swap_b32_e32 v34, v42
	v_permlane32_swap_b32_e32 v35, v43
	v_add_f32_e32 v28, v28, v36
	v_add_f32_e32 v29, v29, v37
	v_add_f32_e32 v30, v30, v38
	v_add_f32_e32 v31, v31, v39
	v_add_f32_e32 v32, v32, v40
	v_add_f32_e32 v33, v33, v41
	v_add_f32_e32 v34, v34, v42
	v_add_f32_e32 v35, v35, v43
	s_nop 1
	v_permlane16_swap_b32_e32 v28, v32
	v_permlane16_swap_b32_e32 v29, v33
	v_permlane16_swap_b32_e32 v30, v34
	v_permlane16_swap_b32_e32 v31, v35
	v_add_f32_e32 v28, v28, v32
	v_add_f32_e32 v29, v29, v33
	v_add_f32_e32 v30, v30, v34
	v_add_f32_e32 v31, v31, v35
	v_cndmask_b32_e64 v116, v28, v30, s[30:31]
	v_cndmask_b32_e64 v117, v30, v28, s[30:31]
	v_cndmask_b32_e64 v122, v29, v31, s[30:31]
	v_cndmask_b32_e64 v123, v31, v29, s[30:31]
	s_nop 1
	v_add_f32_dpp v116, v117, v116 row_ror:8 row_mask:0xf bank_mask:0xf
	v_add_f32_dpp v122, v123, v122 row_ror:8 row_mask:0xf bank_mask:0xf
	s_nop 0
	v_cvt_pk_bf16_f32 v19, v116, v122
	s_lshl_b32 s0, s38, 11
	v_add_u32_e32 v0, s0, v3
	global_store_dword v0, v19, s[48:49]
	s_add_i32 s38, s38, s39
	s_cmp_gt_u32 s38, 0xffff
	s_cbranch_scc1 .Lpv2_part_next

.Lpv2_tokB_in:
	v_mov_b32_e32 v22, v20
	v_mov_b32_e32 v23, v21
	ds_bpermute_b32 v124, v4, v10
	ds_bpermute_b32 v125, v12, v10
	ds_bpermute_b32 v126, v13, v10
	ds_bpermute_b32 v127, v14, v10
	ds_bpermute_b32 v128, v15, v10
	ds_bpermute_b32 v129, v16, v10
	ds_bpermute_b32 v130, v17, v10
	ds_bpermute_b32 v131, v18, v10
	s_waitcnt lgkmcnt(0)
	v_lshl_add_u32 v124, v124, 7, v1
	v_lshl_add_u32 v125, v125, 7, v1
	v_lshl_add_u32 v126, v126, 7, v1
	v_lshl_add_u32 v127, v127, 7, v1
	v_lshl_add_u32 v128, v128, 7, v1
	v_lshl_add_u32 v129, v129, 7, v1
	v_lshl_add_u32 v130, v130, 7, v1
	v_lshl_add_u32 v131, v131, 7, v1
	global_load_dwordx4 v[44:47], v124, s[44:45]
	global_load_dwordx4 v[48:51], v125, s[44:45]
	global_load_dwordx4 v[52:55], v126, s[44:45]
	global_load_dwordx4 v[56:59], v127, s[44:45]
	global_load_dwordx4 v[60:63], v128, s[44:45]
	global_load_dwordx4 v[64:67], v129, s[44:45]
	global_load_dwordx4 v[68:71], v130, s[44:45]
	global_load_dwordx4 v[72:75], v131, s[44:45]
	ds_bpermute_b32 v124, v4, v11
	ds_bpermute_b32 v125, v12, v11
	ds_bpermute_b32 v126, v13, v11
	ds_bpermute_b32 v127, v14, v11
	ds_bpermute_b32 v128, v15, v11
	ds_bpermute_b32 v129, v16, v11
	ds_bpermute_b32 v130, v17, v11
	ds_bpermute_b32 v131, v18, v11
	s_waitcnt lgkmcnt(0)
	v_lshl_add_u32 v124, v124, 7, v1
	v_lshl_add_u32 v125, v125, 7, v1
	v_lshl_add_u32 v126, v126, 7, v1
	v_lshl_add_u32 v127, v127, 7, v1
	v_lshl_add_u32 v128, v128, 7, v1
	v_lshl_add_u32 v129, v129, 7, v1
	v_lshl_add_u32 v130, v130, 7, v1
	v_lshl_add_u32 v131, v131, 7, v1
	global_load_dwordx4 v[76:79], v124, s[44:45]
	global_load_dwordx4 v[80:83], v125, s[44:45]
	global_load_dwordx4 v[84:87], v126, s[44:45]
	global_load_dwordx4 v[88:91], v127, s[44:45]
	global_load_dwordx4 v[92:95], v128, s[44:45]
	global_load_dwordx4 v[96:99], v129, s[44:45]
	global_load_dwordx4 v[100:103], v130, s[44:45]
	global_load_dwordx4 v[104:107], v131, s[44:45]
	s_lshl_b32 s1, s39, 1
	s_add_i32 s1, s1, s38
	s_min_u32 s1, s1, 0xffff
	s_lshl_b32 s0, s1, 9
	v_add_u32_e32 v0, s0, v6
	global_load_dword v10, v0, s[42:43]
	global_load_dword v11, v0, s[42:43] offset:256
	global_load_dword v20, v0, s[46:47]
	global_load_dword v21, v0, s[46:47] offset:256
	ds_bpermute_b32 v238, v4, v24
	ds_bpermute_b32 v239, v12, v24
	ds_bpermute_b32 v240, v13, v24
	ds_bpermute_b32 v241, v14, v24
	ds_bpermute_b32 v242, v15, v24
	ds_bpermute_b32 v243, v16, v24
	ds_bpermute_b32 v244, v17, v24
	ds_bpermute_b32 v245, v18, v24
	ds_bpermute_b32 v108, v4, v25
	ds_bpermute_b32 v109, v12, v25
	ds_bpermute_b32 v110, v13, v25
	ds_bpermute_b32 v111, v14, v25
	ds_bpermute_b32 v112, v15, v25
	ds_bpermute_b32 v113, v16, v25
	ds_bpermute_b32 v114, v17, v25
	ds_bpermute_b32 v115, v18, v25
	s_waitcnt lgkmcnt(0)
	v_cvt_pk_f32_fp8_e32 v[118:119], v198
	v_cvt_pk_f32_fp8_sdwa v[120:121], v198 src0_sel:WORD_1
	s_nop 0
	v_pk_mul_f32 v[28:29], v[118:119], v[238:239] op_sel_hi:[1,0]
	v_cvt_pk_f32_fp8_e32 v[118:119], v199
	v_pk_mul_f32 v[30:31], v[120:121], v[238:239] op_sel_hi:[1,0]
	v_cvt_pk_f32_fp8_sdwa v[120:121], v199 src0_sel:WORD_1
	v_pk_mul_f32 v[32:33], v[118:119], v[238:239] op_sel_hi:[1,0]
	v_cvt_pk_f32_fp8_e32 v[118:119], v200
	v_pk_mul_f32 v[34:35], v[120:121], v[238:239] op_sel_hi:[1,0]
	v_cvt_pk_f32_fp8_sdwa v[120:121], v200 src0_sel:WORD_1
	v_pk_mul_f32 v[36:37], v[118:119], v[238:239] op_sel_hi:[1,0]
	v_cvt_pk_f32_fp8_e32 v[118:119], v201
	v_pk_mul_f32 v[38:39], v[120:121], v[238:239] op_sel_hi:[1,0]
	v_cvt_pk_f32_fp8_sdwa v[120:121], v201 src0_sel:WORD_1
	v_pk_mul_f32 v[40:41], v[118:119], v[238:239] op_sel_hi:[1,0]
	s_nop 0
	v_pk_mul_f32 v[42:43], v[120:121], v[238:239] op_sel_hi:[1,0]
	v_cvt_pk_f32_fp8_e32 v[118:119], v202
	v_cvt_pk_f32_fp8_sdwa v[120:121], v202 src0_sel:WORD_1
	s_nop 0
	v_pk_fma_f32 v[28:29], v[118:119], v[238:239], v[28:29] op_sel:[0,1,0] op_sel_hi:[1,1,1]
	v_cvt_pk_f32_fp8_e32 v[118:119], v203
	v_pk_fma_f32 v[30:31], v[120:121], v[238:239], v[30:31] op_sel:[0,1,0] op_sel_hi:[1,1,1]
	v_cvt_pk_f32_fp8_sdwa v[120:121], v203 src0_sel:WORD_1
	v_pk_fma_f32 v[32:33], v[118:119], v[238:239], v[32:33] op_sel:[0,1,0] op_sel_hi:[1,1,1]
	v_cvt_pk_f32_fp8_e32 v[118:119], v204
	v_pk_fma_f32 v[34:35], v[120:121], v[238:239], v[34:35] op_sel:[0,1,0] op_sel_hi:[1,1,1]
	v_cvt_pk_f32_fp8_sdwa v[120:121], v204 src0_sel:WORD_1
	v_pk_fma_f32 v[36:37], v[118:119], v[238:239], v[36:37] op_sel:[0,1,0] op_sel_hi:[1,1,1]
	v_cvt_pk_f32_fp8_e32 v[118:119], v205
	v_pk_fma_f32 v[38:39], v[120:121], v[238:239], v[38:39] op_sel:[0,1,0] op_sel_hi:[1,1,1]
	v_cvt_pk_f32_fp8_sdwa v[120:121], v205 src0_sel:WORD_1
	v_pk_fma_f32 v[40:41], v[118:119], v[238:239], v[40:41] op_sel:[0,1,0] op_sel_hi:[1,1,1]
	s_nop 0
	v_pk_fma_f32 v[42:43], v[120:121], v[238:239], v[42:43] op_sel:[0,1,0] op_sel_hi:[1,1,1]
	v_cvt_pk_f32_fp8_e32 v[118:119], v206
	v_cvt_pk_f32_fp8_sdwa v[120:121], v206 src0_sel:WORD_1
	s_nop 0
	v_pk_fma_f32 v[28:29], v[118:119], v[240:241], v[28:29] op_sel_hi:[1,0,1]
	v_cvt_pk_f32_fp8_e32 v[118:119], v207
	v_pk_fma_f32 v[30:31], v[120:121], v[240:241], v[30:31] op_sel_hi:[1,0,1]
	v_cvt_pk_f32_fp8_sdwa v[120:121], v207 src0_sel:WORD_1
	v_pk_fma_f32 v[32:33], v[118:119], v[240:241], v[32:33] op_sel_hi:[1,0,1]
	v_cvt_pk_f32_fp8_e32 v[118:119], v208
	v_pk_fma_f32 v[34:35], v[120:121], v[240:241], v[34:35] op_sel_hi:[1,0,1]
	v_cvt_pk_f32_fp8_sdwa v[120:121], v208 src0_sel:WORD_1
	v_pk_fma_f32 v[36:37], v[118:119], v[240:241], v[36:37] op_sel_hi:[1,0,1]
	v_cvt_pk_f32_fp8_e32 v[118:119], v209
	v_pk_fma_f32 v[38:39], v[120:121], v[240:241], v[38:39] op_sel_hi:[1,0,1]
	v_cvt_pk_f32_fp8_sdwa v[120:121], v209 src0_sel:WORD_1
	v_pk_fma_f32 v[40:41], v[118:119], v[240:241], v[40:41] op_sel_hi:[1,0,1]
	s_nop 0
	v_pk_fma_f32 v[42:43], v[120:121], v[240:241], v[42:43] op_sel_hi:[1,0,1]
	v_cvt_pk_f32_fp8_e32 v[118:119], v210
	v_cvt_pk_f32_fp8_sdwa v[120:121], v210 src0_sel:WORD_1
	s_nop 0
	v_pk_fma_f32 v[28:29], v[118:119], v[240:241], v[28:29] op_sel:[0,1,0] op_sel_hi:[1,1,1]
	v_cvt_pk_f32_fp8_e32 v[118:119], v211
	v_pk_fma_f32 v[30:31], v[120:121], v[240:241], v[30:31] op_sel:[0,1,0] op_sel_hi:[1,1,1]
	v_cvt_pk_f32_fp8_sdwa v[120:121], v211 src0_sel:WORD_1
	v_pk_fma_f32 v[32:33], v[118:119], v[240:241], v[32:33] op_sel:[0,1,0] op_sel_hi:[1,1,1]
	v_cvt_pk_f32_fp8_e32 v[118:119], v212
	v_pk_fma_f32 v[34:35], v[120:121], v[240:241], v[34:35] op_sel:[0,1,0] op_sel_hi:[1,1,1]
	v_cvt_pk_f32_fp8_sdwa v[120:121], v212 src0_sel:WORD_1
	v_pk_fma_f32 v[36:37], v[118:119], v[240:241], v[36:37] op_sel:[0,1,0] op_sel_hi:[1,1,1]
	v_cvt_pk_f32_fp8_e32 v[118:119], v213
	v_pk_fma_f32 v[38:39], v[120:121], v[240:241], v[38:39] op_sel:[0,1,0] op_sel_hi:[1,1,1]
	v_cvt_pk_f32_fp8_sdwa v[120:121], v213 src0_sel:WORD_1
	v_pk_fma_f32 v[40:41], v[118:119], v[240:241], v[40:41] op_sel:[0,1,0] op_sel_hi:[1,1,1]
	s_nop 0
	v_pk_fma_f32 v[42:43], v[120:121], v[240:241], v[42:43] op_sel:[0,1,0] op_sel_hi:[1,1,1]
	v_cvt_pk_f32_fp8_e32 v[118:119], v214
	v_cvt_pk_f32_fp8_sdwa v[120:121], v214 src0_sel:WORD_1
	s_nop 0
	v_pk_fma_f32 v[28:29], v[118:119], v[242:243], v[28:29] op_sel_hi:[1,0,1]
	v_cvt_pk_f32_fp8_e32 v[118:119], v215
	v_pk_fma_f32 v[30:31], v[120:121], v[242:243], v[30:31] op_sel_hi:[1,0,1]
	v_cvt_pk_f32_fp8_sdwa v[120:121], v215 src0_sel:WORD_1
	v_pk_fma_f32 v[32:33], v[118:119], v[242:243], v[32:33] op_sel_hi:[1,0,1]
	v_cvt_pk_f32_fp8_e32 v[118:119], v216
	v_pk_fma_f32 v[34:35], v[120:121], v[242:243], v[34:35] op_sel_hi:[1,0,1]
	v_cvt_pk_f32_fp8_sdwa v[120:121], v216 src0_sel:WORD_1
	v_pk_fma_f32 v[36:37], v[118:119], v[242:243], v[36:37] op_sel_hi:[1,0,1]
	v_cvt_pk_f32_fp8_e32 v[118:119], v217
	v_pk_fma_f32 v[38:39], v[120:121], v[242:243], v[38:39] op_sel_hi:[1,0,1]
	v_cvt_pk_f32_fp8_sdwa v[120:121], v217 src0_sel:WORD_1
	v_pk_fma_f32 v[40:41], v[118:119], v[242:243], v[40:41] op_sel_hi:[1,0,1]
	s_nop 0
	v_pk_fma_f32 v[42:43], v[120:121], v[242:243], v[42:43] op_sel_hi:[1,0,1]
	v_cvt_pk_f32_fp8_e32 v[118:119], v218
	v_cvt_pk_f32_fp8_sdwa v[120:121], v218 src0_sel:WORD_1
	s_nop 0
	v_pk_fma_f32 v[28:29], v[118:119], v[242:243], v[28:29] op_sel:[0,1,0] op_sel_hi:[1,1,1]
	v_cvt_pk_f32_fp8_e32 v[118:119], v219
	v_pk_fma_f32 v[30:31], v[120:121], v[242:243], v[30:31] op_sel:[0,1,0] op_sel_hi:[1,1,1]
	v_cvt_pk_f32_fp8_sdwa v[120:121], v219 src0_sel:WORD_1
	v_pk_fma_f32 v[32:33], v[118:119], v[242:243], v[32:33] op_sel:[0,1,0] op_sel_hi:[1,1,1]
	v_cvt_pk_f32_fp8_e32 v[118:119], v220
	v_pk_fma_f32 v[34:35], v[120:121], v[242:243], v[34:35] op_sel:[0,1,0] op_sel_hi:[1,1,1]
	v_cvt_pk_f32_fp8_sdwa v[120:121], v220 src0_sel:WORD_1
	v_pk_fma_f32 v[36:37], v[118:119], v[242:243], v[36:37] op_sel:[0,1,0] op_sel_hi:[1,1,1]
	v_cvt_pk_f32_fp8_e32 v[118:119], v221
	v_pk_fma_f32 v[38:39], v[120:121], v[242:243], v[38:39] op_sel:[0,1,0] op_sel_hi:[1,1,1]
	v_cvt_pk_f32_fp8_sdwa v[120:121], v221 src0_sel:WORD_1
	v_pk_fma_f32 v[40:41], v[118:119], v[242:243], v[40:41] op_sel:[0,1,0] op_sel_hi:[1,1,1]
	s_nop 0
	v_pk_fma_f32 v[42:43], v[120:121], v[242:243], v[42:43] op_sel:[0,1,0] op_sel_hi:[1,1,1]
	v_cvt_pk_f32_fp8_e32 v[118:119], v222
	v_cvt_pk_f32_fp8_sdwa v[120:121], v222 src0_sel:WORD_1
	s_nop 0
	v_pk_fma_f32 v[28:29], v[118:119], v[244:245], v[28:29] op_sel_hi:[1,0,1]
	v_cvt_pk_f32_fp8_e32 v[118:119], v223
	v_pk_fma_f32 v[30:31], v[120:121], v[244:245], v[30:31] op_sel_hi:[1,0,1]
	v_cvt_pk_f32_fp8_sdwa v[120:121], v223 src0_sel:WORD_1
	v_pk_fma_f32 v[32:33], v[118:119], v[244:245], v[32:33] op_sel_hi:[1,0,1]
	v_cvt_pk_f32_fp8_e32 v[118:119], v224
	v_pk_fma_f32 v[34:35], v[120:121], v[244:245], v[34:35] op_sel_hi:[1,0,1]
	v_cvt_pk_f32_fp8_sdwa v[120:121], v224 src0_sel:WORD_1
	v_pk_fma_f32 v[36:37], v[118:119], v[244:245], v[36:37] op_sel_hi:[1,0,1]
	v_cvt_pk_f32_fp8_e32 v[118:119], v225
	v_pk_fma_f32 v[38:39], v[120:121], v[244:245], v[38:39] op_sel_hi:[1,0,1]
	v_cvt_pk_f32_fp8_sdwa v[120:121], v225 src0_sel:WORD_1
	v_pk_fma_f32 v[40:41], v[118:119], v[244:245], v[40:41] op_sel_hi:[1,0,1]
	s_nop 0
	v_pk_fma_f32 v[42:43], v[120:121], v[244:245], v[42:43] op_sel_hi:[1,0,1]
	v_cvt_pk_f32_fp8_e32 v[118:119], v226
	v_cvt_pk_f32_fp8_sdwa v[120:121], v226 src0_sel:WORD_1
	s_nop 0
	v_pk_fma_f32 v[28:29], v[118:119], v[244:245], v[28:29] op_sel:[0,1,0] op_sel_hi:[1,1,1]
	v_cvt_pk_f32_fp8_e32 v[118:119], v227
	v_pk_fma_f32 v[30:31], v[120:121], v[244:245], v[30:31] op_sel:[0,1,0] op_sel_hi:[1,1,1]
	v_cvt_pk_f32_fp8_sdwa v[120:121], v227 src0_sel:WORD_1
	v_pk_fma_f32 v[32:33], v[118:119], v[244:245], v[32:33] op_sel:[0,1,0] op_sel_hi:[1,1,1]
	v_cvt_pk_f32_fp8_e32 v[118:119], v228
	v_pk_fma_f32 v[34:35], v[120:121], v[244:245], v[34:35] op_sel:[0,1,0] op_sel_hi:[1,1,1]
	v_cvt_pk_f32_fp8_sdwa v[120:121], v228 src0_sel:WORD_1
	v_pk_fma_f32 v[36:37], v[118:119], v[244:245], v[36:37] op_sel:[0,1,0] op_sel_hi:[1,1,1]
	v_cvt_pk_f32_fp8_e32 v[118:119], v229
	v_pk_fma_f32 v[38:39], v[120:121], v[244:245], v[38:39] op_sel:[0,1,0] op_sel_hi:[1,1,1]
	v_cvt_pk_f32_fp8_sdwa v[120:121], v229 src0_sel:WORD_1
	v_pk_fma_f32 v[40:41], v[118:119], v[244:245], v[40:41] op_sel:[0,1,0] op_sel_hi:[1,1,1]
	s_nop 0
	v_pk_fma_f32 v[42:43], v[120:121], v[244:245], v[42:43] op_sel:[0,1,0] op_sel_hi:[1,1,1]
	v_cvt_pk_f32_fp8_e32 v[118:119], v230
	v_cvt_pk_f32_fp8_sdwa v[120:121], v230 src0_sel:WORD_1
	s_nop 0
	v_pk_fma_f32 v[28:29], v[118:119], v[108:109], v[28:29] op_sel_hi:[1,0,1]
	v_cvt_pk_f32_fp8_e32 v[118:119], v231
	v_pk_fma_f32 v[30:31], v[120:121], v[108:109], v[30:31] op_sel_hi:[1,0,1]
	v_cvt_pk_f32_fp8_sdwa v[120:121], v231 src0_sel:WORD_1
	v_pk_fma_f32 v[32:33], v[118:119], v[108:109], v[32:33] op_sel_hi:[1,0,1]
	v_cvt_pk_f32_fp8_e32 v[118:119], v232
	v_pk_fma_f32 v[34:35], v[120:121], v[108:109], v[34:35] op_sel_hi:[1,0,1]
	v_cvt_pk_f32_fp8_sdwa v[120:121], v232 src0_sel:WORD_1
	v_pk_fma_f32 v[36:37], v[118:119], v[108:109], v[36:37] op_sel_hi:[1,0,1]
	v_cvt_pk_f32_fp8_e32 v[118:119], v233
	v_pk_fma_f32 v[38:39], v[120:121], v[108:109], v[38:39] op_sel_hi:[1,0,1]
	v_cvt_pk_f32_fp8_sdwa v[120:121], v233 src0_sel:WORD_1
	v_pk_fma_f32 v[40:41], v[118:119], v[108:109], v[40:41] op_sel_hi:[1,0,1]
	s_nop 0
	v_pk_fma_f32 v[42:43], v[120:121], v[108:109], v[42:43] op_sel_hi:[1,0,1]
	v_cvt_pk_f32_fp8_e32 v[118:119], v234
	v_cvt_pk_f32_fp8_sdwa v[120:121], v234 src0_sel:WORD_1
	s_nop 0
	v_pk_fma_f32 v[28:29], v[118:119], v[108:109], v[28:29] op_sel:[0,1,0] op_sel_hi:[1,1,1]
	v_cvt_pk_f32_fp8_e32 v[118:119], v235
	v_pk_fma_f32 v[30:31], v[120:121], v[108:109], v[30:31] op_sel:[0,1,0] op_sel_hi:[1,1,1]
	v_cvt_pk_f32_fp8_sdwa v[120:121], v235 src0_sel:WORD_1
	v_pk_fma_f32 v[32:33], v[118:119], v[108:109], v[32:33] op_sel:[0,1,0] op_sel_hi:[1,1,1]
	v_cvt_pk_f32_fp8_e32 v[118:119], v236
	v_pk_fma_f32 v[34:35], v[120:121], v[108:109], v[34:35] op_sel:[0,1,0] op_sel_hi:[1,1,1]
	v_cvt_pk_f32_fp8_sdwa v[120:121], v236 src0_sel:WORD_1
	v_pk_fma_f32 v[36:37], v[118:119], v[108:109], v[36:37] op_sel:[0,1,0] op_sel_hi:[1,1,1]
	v_cvt_pk_f32_fp8_e32 v[118:119], v237
	v_pk_fma_f32 v[38:39], v[120:121], v[108:109], v[38:39] op_sel:[0,1,0] op_sel_hi:[1,1,1]
	v_cvt_pk_f32_fp8_sdwa v[120:121], v237 src0_sel:WORD_1
	v_pk_fma_f32 v[40:41], v[118:119], v[108:109], v[40:41] op_sel:[0,1,0] op_sel_hi:[1,1,1]
	s_nop 0
	v_pk_fma_f32 v[42:43], v[120:121], v[108:109], v[42:43] op_sel:[0,1,0] op_sel_hi:[1,1,1]
	v_cvt_pk_f32_fp8_e32 v[118:119], v138
	v_cvt_pk_f32_fp8_sdwa v[120:121], v138 src0_sel:WORD_1
	s_nop 0
	v_pk_fma_f32 v[28:29], v[118:119], v[110:111], v[28:29] op_sel_hi:[1,0,1]
	v_cvt_pk_f32_fp8_e32 v[118:119], v139
	v_pk_fma_f32 v[30:31], v[120:121], v[110:111], v[30:31] op_sel_hi:[1,0,1]
	v_cvt_pk_f32_fp8_sdwa v[120:121], v139 src0_sel:WORD_1
	v_pk_fma_f32 v[32:33], v[118:119], v[110:111], v[32:33] op_sel_hi:[1,0,1]
	v_cvt_pk_f32_fp8_e32 v[118:119], v140
	v_pk_fma_f32 v[34:35], v[120:121], v[110:111], v[34:35] op_sel_hi:[1,0,1]
	v_cvt_pk_f32_fp8_sdwa v[120:121], v140 src0_sel:WORD_1
	v_pk_fma_f32 v[36:37], v[118:119], v[110:111], v[36:37] op_sel_hi:[1,0,1]
	v_cvt_pk_f32_fp8_e32 v[118:119], v141
	v_pk_fma_f32 v[38:39], v[120:121], v[110:111], v[38:39] op_sel_hi:[1,0,1]
	v_cvt_pk_f32_fp8_sdwa v[120:121], v141 src0_sel:WORD_1
	v_pk_fma_f32 v[40:41], v[118:119], v[110:111], v[40:41] op_sel_hi:[1,0,1]
	s_nop 0
	v_pk_fma_f32 v[42:43], v[120:121], v[110:111], v[42:43] op_sel_hi:[1,0,1]
	v_cvt_pk_f32_fp8_e32 v[118:119], v142
	v_cvt_pk_f32_fp8_sdwa v[120:121], v142 src0_sel:WORD_1
	s_nop 0
	v_pk_fma_f32 v[28:29], v[118:119], v[110:111], v[28:29] op_sel:[0,1,0] op_sel_hi:[1,1,1]
	v_cvt_pk_f32_fp8_e32 v[118:119], v143
	v_pk_fma_f32 v[30:31], v[120:121], v[110:111], v[30:31] op_sel:[0,1,0] op_sel_hi:[1,1,1]
	v_cvt_pk_f32_fp8_sdwa v[120:121], v143 src0_sel:WORD_1
	v_pk_fma_f32 v[32:33], v[118:119], v[110:111], v[32:33] op_sel:[0,1,0] op_sel_hi:[1,1,1]
	v_cvt_pk_f32_fp8_e32 v[118:119], v144
	v_pk_fma_f32 v[34:35], v[120:121], v[110:111], v[34:35] op_sel:[0,1,0] op_sel_hi:[1,1,1]
	v_cvt_pk_f32_fp8_sdwa v[120:121], v144 src0_sel:WORD_1
	v_pk_fma_f32 v[36:37], v[118:119], v[110:111], v[36:37] op_sel:[0,1,0] op_sel_hi:[1,1,1]
	v_cvt_pk_f32_fp8_e32 v[118:119], v145
	v_pk_fma_f32 v[38:39], v[120:121], v[110:111], v[38:39] op_sel:[0,1,0] op_sel_hi:[1,1,1]
	v_cvt_pk_f32_fp8_sdwa v[120:121], v145 src0_sel:WORD_1
	v_pk_fma_f32 v[40:41], v[118:119], v[110:111], v[40:41] op_sel:[0,1,0] op_sel_hi:[1,1,1]
	s_nop 0
	v_pk_fma_f32 v[42:43], v[120:121], v[110:111], v[42:43] op_sel:[0,1,0] op_sel_hi:[1,1,1]
	v_cvt_pk_f32_fp8_e32 v[118:119], v146
	v_cvt_pk_f32_fp8_sdwa v[120:121], v146 src0_sel:WORD_1
	s_nop 0
	v_pk_fma_f32 v[28:29], v[118:119], v[112:113], v[28:29] op_sel_hi:[1,0,1]
	v_cvt_pk_f32_fp8_e32 v[118:119], v147
	v_pk_fma_f32 v[30:31], v[120:121], v[112:113], v[30:31] op_sel_hi:[1,0,1]
	v_cvt_pk_f32_fp8_sdwa v[120:121], v147 src0_sel:WORD_1
	v_pk_fma_f32 v[32:33], v[118:119], v[112:113], v[32:33] op_sel_hi:[1,0,1]
	v_cvt_pk_f32_fp8_e32 v[118:119], v148
	v_pk_fma_f32 v[34:35], v[120:121], v[112:113], v[34:35] op_sel_hi:[1,0,1]
	v_cvt_pk_f32_fp8_sdwa v[120:121], v148 src0_sel:WORD_1
	v_pk_fma_f32 v[36:37], v[118:119], v[112:113], v[36:37] op_sel_hi:[1,0,1]
	v_cvt_pk_f32_fp8_e32 v[118:119], v149
	v_pk_fma_f32 v[38:39], v[120:121], v[112:113], v[38:39] op_sel_hi:[1,0,1]
	v_cvt_pk_f32_fp8_sdwa v[120:121], v149 src0_sel:WORD_1
	v_pk_fma_f32 v[40:41], v[118:119], v[112:113], v[40:41] op_sel_hi:[1,0,1]
	s_nop 0
	v_pk_fma_f32 v[42:43], v[120:121], v[112:113], v[42:43] op_sel_hi:[1,0,1]
	v_cvt_pk_f32_fp8_e32 v[118:119], v150
	v_cvt_pk_f32_fp8_sdwa v[120:121], v150 src0_sel:WORD_1
	s_nop 0
	v_pk_fma_f32 v[28:29], v[118:119], v[112:113], v[28:29] op_sel:[0,1,0] op_sel_hi:[1,1,1]
	v_cvt_pk_f32_fp8_e32 v[118:119], v151
	v_pk_fma_f32 v[30:31], v[120:121], v[112:113], v[30:31] op_sel:[0,1,0] op_sel_hi:[1,1,1]
	v_cvt_pk_f32_fp8_sdwa v[120:121], v151 src0_sel:WORD_1
	v_pk_fma_f32 v[32:33], v[118:119], v[112:113], v[32:33] op_sel:[0,1,0] op_sel_hi:[1,1,1]
	v_cvt_pk_f32_fp8_e32 v[118:119], v152
	v_pk_fma_f32 v[34:35], v[120:121], v[112:113], v[34:35] op_sel:[0,1,0] op_sel_hi:[1,1,1]
	v_cvt_pk_f32_fp8_sdwa v[120:121], v152 src0_sel:WORD_1
	v_pk_fma_f32 v[36:37], v[118:119], v[112:113], v[36:37] op_sel:[0,1,0] op_sel_hi:[1,1,1]
	v_cvt_pk_f32_fp8_e32 v[118:119], v153
	v_pk_fma_f32 v[38:39], v[120:121], v[112:113], v[38:39] op_sel:[0,1,0] op_sel_hi:[1,1,1]
	v_cvt_pk_f32_fp8_sdwa v[120:121], v153 src0_sel:WORD_1
	v_pk_fma_f32 v[40:41], v[118:119], v[112:113], v[40:41] op_sel:[0,1,0] op_sel_hi:[1,1,1]
	s_nop 0
	v_pk_fma_f32 v[42:43], v[120:121], v[112:113], v[42:43] op_sel:[0,1,0] op_sel_hi:[1,1,1]
	v_cvt_pk_f32_fp8_e32 v[118:119], v154
	v_cvt_pk_f32_fp8_sdwa v[120:121], v154 src0_sel:WORD_1
	s_nop 0
	v_pk_fma_f32 v[28:29], v[118:119], v[114:115], v[28:29] op_sel_hi:[1,0,1]
	v_cvt_pk_f32_fp8_e32 v[118:119], v155
	v_pk_fma_f32 v[30:31], v[120:121], v[114:115], v[30:31] op_sel_hi:[1,0,1]
	v_cvt_pk_f32_fp8_sdwa v[120:121], v155 src0_sel:WORD_1
	v_pk_fma_f32 v[32:33], v[118:119], v[114:115], v[32:33] op_sel_hi:[1,0,1]
	v_cvt_pk_f32_fp8_e32 v[118:119], v156
	v_pk_fma_f32 v[34:35], v[120:121], v[114:115], v[34:35] op_sel_hi:[1,0,1]
	v_cvt_pk_f32_fp8_sdwa v[120:121], v156 src0_sel:WORD_1
	v_pk_fma_f32 v[36:37], v[118:119], v[114:115], v[36:37] op_sel_hi:[1,0,1]
	v_cvt_pk_f32_fp8_e32 v[118:119], v157
	v_pk_fma_f32 v[38:39], v[120:121], v[114:115], v[38:39] op_sel_hi:[1,0,1]
	v_cvt_pk_f32_fp8_sdwa v[120:121], v157 src0_sel:WORD_1
	v_pk_fma_f32 v[40:41], v[118:119], v[114:115], v[40:41] op_sel_hi:[1,0,1]
	s_nop 0
	v_pk_fma_f32 v[42:43], v[120:121], v[114:115], v[42:43] op_sel_hi:[1,0,1]
	v_cvt_pk_f32_fp8_e32 v[118:119], v158
	v_cvt_pk_f32_fp8_sdwa v[120:121], v158 src0_sel:WORD_1
	s_nop 0
	v_pk_fma_f32 v[28:29], v[118:119], v[114:115], v[28:29] op_sel:[0,1,0] op_sel_hi:[1,1,1]
	v_cvt_pk_f32_fp8_e32 v[118:119], v159
	v_pk_fma_f32 v[30:31], v[120:121], v[114:115], v[30:31] op_sel:[0,1,0] op_sel_hi:[1,1,1]
	v_cvt_pk_f32_fp8_sdwa v[120:121], v159 src0_sel:WORD_1
	v_pk_fma_f32 v[32:33], v[118:119], v[114:115], v[32:33] op_sel:[0,1,0] op_sel_hi:[1,1,1]
	v_cvt_pk_f32_fp8_e32 v[118:119], v160
	v_pk_fma_f32 v[34:35], v[120:121], v[114:115], v[34:35] op_sel:[0,1,0] op_sel_hi:[1,1,1]
	v_cvt_pk_f32_fp8_sdwa v[120:121], v160 src0_sel:WORD_1
	v_pk_fma_f32 v[36:37], v[118:119], v[114:115], v[36:37] op_sel:[0,1,0] op_sel_hi:[1,1,1]
	v_cvt_pk_f32_fp8_e32 v[118:119], v161
	v_pk_fma_f32 v[38:39], v[120:121], v[114:115], v[38:39] op_sel:[0,1,0] op_sel_hi:[1,1,1]
	v_cvt_pk_f32_fp8_sdwa v[120:121], v161 src0_sel:WORD_1
	v_pk_fma_f32 v[40:41], v[118:119], v[114:115], v[40:41] op_sel:[0,1,0] op_sel_hi:[1,1,1]
	s_nop 0
	v_pk_fma_f32 v[42:43], v[120:121], v[114:115], v[42:43] op_sel:[0,1,0] op_sel_hi:[1,1,1]
	s_nop 1
	v_permlane32_swap_b32_e32 v28, v36
	v_permlane32_swap_b32_e32 v29, v37
	v_permlane32_swap_b32_e32 v30, v38
	v_permlane32_swap_b32_e32 v31, v39
	v_permlane32_swap_b32_e32 v32, v40
	v_permlane32_swap_b32_e32 v33, v41
	v_permlane32_swap_b32_e32 v34, v42
	v_permlane32_swap_b32_e32 v35, v43
	v_add_f32_e32 v28, v28, v36
	v_add_f32_e32 v29, v29, v37
	v_add_f32_e32 v30, v30, v38
	v_add_f32_e32 v31, v31, v39
	v_add_f32_e32 v32, v32, v40
	v_add_f32_e32 v33, v33, v41
	v_add_f32_e32 v34, v34, v42
	v_add_f32_e32 v35, v35, v43
	s_nop 1
	v_permlane16_swap_b32_e32 v28, v32
	v_permlane16_swap_b32_e32 v29, v33
	v_permlane16_swap_b32_e32 v30, v34
	v_permlane16_swap_b32_e32 v31, v35
	v_add_f32_e32 v28, v28, v32
	v_add_f32_e32 v29, v29, v33
	v_add_f32_e32 v30, v30, v34
	v_add_f32_e32 v31, v31, v35
	v_cndmask_b32_e64 v116, v28, v30, s[30:31]
	v_cndmask_b32_e64 v117, v30, v28, s[30:31]
	v_cndmask_b32_e64 v122, v29, v31, s[30:31]
	v_cndmask_b32_e64 v123, v31, v29, s[30:31]
	s_nop 1
	v_add_f32_dpp v116, v117, v116 row_ror:8 row_mask:0xf bank_mask:0xf
	v_add_f32_dpp v122, v123, v122 row_ror:8 row_mask:0xf bank_mask:0xf
	s_nop 0
	v_cvt_pk_bf16_f32 v19, v116, v122
	s_lshl_b32 s0, s38, 11
	v_add_u32_e32 v0, s0, v3
	global_store_dword v0, v19, s[48:49]
	s_add_i32 s38, s38, s39
	s_cmp_gt_u32 s38, 0xffff
	s_cbranch_scc1 .Lpv2_part_next
	s_branch .Lpv2_tokA
